# attention stage loops (O3, E4, xattn): tm = max(tm, shfl_xor(tm,32)) via v_permlane32_swap instead of ds_bpermute + immediate lgkmcnt(0) wait (6 sites)
# speedup vs baseline: 1.0339x; 1.0045x over previous
; #define LAS __attribute__((address_space(3)))
; template <int DQK, int DV, int MODE, bool QNORM, int SK, int NQ> ...
;     ...
; #pragma unroll
;             for (int qh = 0; qh < NQ; ++qh)
; #pragma unroll
;                 for (int sub = 0; sub < NSUB; ++sub)
; #pragma unroll
;                     for (int r = 0; r < 16; ++r) sc[qh][sub][r] = QNORM ? 0.f : -m_run[qh];
;             if (NQ == 1 && DQK <= 96) {
;                 bf16x8 kfa[NSUB][DQK / 16];
; #pragma unroll
;                 for (int d0 = 0; d0 < DQK / 16; ++d0)
; #pragma unroll
;                     for (int sub = 0; sub < NSUB; ++sub) kfa[sub][d0] = *(const LAS bf16x8*)(sb + (sub * 32 + r32) * KP + hi * 16 + d0 * 32);
;                 asm volatile("s_waitcnt lgkmcnt(0)" ::: "memory");
;                 __builtin_amdgcn_sched_barrier(0);
;                 __builtin_amdgcn_s_setprio(1);
; #pragma unroll
;                 for (int d0 = 0; d0 < DQK / 16; ++d0)
; #pragma unroll
;                     for (int sub = 0; sub < NSUB; ++sub) sc[0][sub] = __builtin_amdgcn_mfma_f32_32x32x16_bf16(kfa[sub][d0], qf[0][d0], sc[0][sub], 0, 0, 0);
;             } else {
;             __builtin_amdgcn_s_setprio(1);
; #pragma unroll
;             for (int d0 = 0; d0 < DQK / 16; ++d0)
; #pragma unroll
;                 for (int sub = 0; sub < NSUB; ++sub) {
;                     const bf16x8 kf = *(const LAS bf16x8*)(sb + (sub * 32 + r32) * KP + hi * 16 + d0 * 32);
; #pragma unroll
;                     for (int qh = 0; qh < NQ; ++qh) sc[qh][sub] = __builtin_amdgcn_mfma_f32_32x32x16_bf16(kf, qf[qh][d0], sc[qh][sub], 0, 0, 0);
;     ...
;                 } else if (MODE == 1) {
;                     const unsigned w = sub ? wcur1 : wcur0;
; #pragma unroll
;                     for (int r = 0; r < 16; ++r) { if (((w >> crow(r, hi)) & 1u) == 0u) {
; #pragma unroll
;                         for (int qh = 0; qh < NQ; ++qh) sc[qh][sub][r] = -INFINITY; } }
;                 } else if (st >= nst_w) {
; #pragma unroll
;                     for (int qh = 0; qh < NQ; ++qh)
; #pragma unroll
;                         for (int r = 0; r < 16; ++r) sc[qh][sub][r] = -INFINITY;
;                 }
;             }
;             bf16x8 pf[NQ][NSUB][2];
; #pragma unroll
;             for (int qh = 0; qh < NQ; ++qh) {
;                 float tm = sc[qh][0][0];
; #pragma unroll
;                 for (int sub = 0; sub < NSUB; ++sub)
; #pragma unroll
.LBB0_3901:
	s_bitcmp1_b32 s8, 0
	s_cselect_b32 s0, 0x4800, 0
	v_xor_b32_e32 v66, 0x80000000, v248
	s_add_i32 s85, s0, 0
	v_xor_b32_e32 v98, 0x80000000, v247
	v_mov_b32_e32 v67, v66
	v_mov_b32_e32 v68, v66
	v_mov_b32_e32 v69, v66
	v_mov_b32_e32 v70, v66
	v_mov_b32_e32 v71, v66
	v_mov_b32_e32 v72, v66
	v_mov_b32_e32 v73, v66
	v_mov_b32_e32 v74, v66
	v_mov_b32_e32 v75, v66
	v_mov_b32_e32 v76, v66
	v_mov_b32_e32 v77, v66
	v_mov_b32_e32 v78, v66
	v_mov_b32_e32 v79, v66
	v_mov_b32_e32 v80, v66
	v_mov_b32_e32 v81, v66
	v_mov_b32_e32 v99, v98
	v_mov_b32_e32 v100, v98
	v_mov_b32_e32 v101, v98
	v_mov_b32_e32 v102, v98
	v_mov_b32_e32 v103, v98
	v_mov_b32_e32 v104, v98
	v_mov_b32_e32 v105, v98
	v_mov_b32_e32 v106, v98
	v_mov_b32_e32 v107, v98
	v_mov_b32_e32 v108, v98
	v_mov_b32_e32 v109, v98
	v_mov_b32_e32 v110, v98
	v_mov_b32_e32 v111, v98
	v_mov_b32_e32 v112, v98
	v_mov_b32_e32 v113, v98
	s_setprio 1
	v_add3_u32 v190, s85, v170, v171
	ds_read_b128 v[186:189], v190
	s_waitcnt lgkmcnt(0)
	v_mfma_f32_32x32x16_bf16 v[114:129], v[186:189], v[130:133], v[98:113]
	v_mfma_f32_32x32x16_bf16 v[82:97], v[186:189], v[146:149], v[66:81]
	ds_read_b128 v[186:189], v190 offset:4608
	s_waitcnt lgkmcnt(0)
	v_mfma_f32_32x32x16_bf16 v[98:113], v[186:189], v[130:133], v[98:113]
	v_mfma_f32_32x32x16_bf16 v[66:81], v[186:189], v[146:149], v[66:81]
	ds_read_b128 v[186:189], v190 offset:32
	s_waitcnt lgkmcnt(0)
	v_mfma_f32_32x32x16_bf16 v[114:129], v[186:189], v[134:137], v[114:129]
	v_mfma_f32_32x32x16_bf16 v[82:97], v[186:189], v[150:153], v[82:97]
	ds_read_b128 v[186:189], v190 offset:4640
	s_waitcnt lgkmcnt(0)
	v_mfma_f32_32x32x16_bf16 v[98:113], v[186:189], v[134:137], v[98:113]
	v_mfma_f32_32x32x16_bf16 v[66:81], v[186:189], v[150:153], v[66:81]
	ds_read_b128 v[186:189], v190 offset:64
	s_waitcnt lgkmcnt(0)
	v_mfma_f32_32x32x16_bf16 v[114:129], v[186:189], v[138:141], v[114:129]
	v_mfma_f32_32x32x16_bf16 v[82:97], v[186:189], v[154:157], v[82:97]
	ds_read_b128 v[186:189], v190 offset:4672
	s_waitcnt lgkmcnt(0)
	v_mfma_f32_32x32x16_bf16 v[98:113], v[186:189], v[138:141], v[98:113]
	v_mfma_f32_32x32x16_bf16 v[66:81], v[186:189], v[154:157], v[66:81]
	ds_read_b128 v[186:189], v190 offset:96
	s_waitcnt lgkmcnt(0)
	v_mfma_f32_32x32x16_bf16 v[114:129], v[186:189], v[142:145], v[114:129]
	v_mfma_f32_32x32x16_bf16 v[82:97], v[186:189], v[158:161], v[82:97]
	ds_read_b128 v[186:189], v190 offset:4704
	s_waitcnt lgkmcnt(0)
	v_mfma_f32_32x32x16_bf16 v[98:113], v[186:189], v[142:145], v[98:113]
	v_mfma_f32_32x32x16_bf16 v[66:81], v[186:189], v[158:161], v[66:81]
	s_setprio 0
	s_nop 0
	v_and_b32_e32 v186, v245, v203
	v_cmp_eq_u32_e64 s[0:1], 0, v186
	v_and_b32_e32 v186, v245, v204
	v_cmp_eq_u32_e64 s[70:71], 0, v186
	v_and_b32_e32 v186, v245, v205
	v_cmp_eq_u32_e64 s[8:9], 0, v186
	v_and_b32_e32 v186, v245, v206
	v_cmp_eq_u32_e64 s[10:11], 0, v186
	v_and_b32_e32 v186, v245, v207
	v_cmp_eq_u32_e64 s[12:13], 0, v186
	v_and_b32_e32 v186, v245, v208
	v_cmp_eq_u32_e64 s[14:15], 0, v186
	v_and_b32_e32 v186, v245, v209
	v_cmp_eq_u32_e64 s[16:17], 0, v186
	v_and_b32_e32 v186, v245, v210
	v_cmp_eq_u32_e64 s[18:19], 0, v186
	v_and_b32_e32 v186, v245, v211
	v_cmp_eq_u32_e64 s[20:21], 0, v186
	v_and_b32_e32 v186, v245, v212
	v_cmp_eq_u32_e64 s[22:23], 0, v186
	v_and_b32_e32 v186, v245, v213
	v_cmp_eq_u32_e64 s[24:25], 0, v186
	v_and_b32_e32 v186, v245, v214
	v_cmp_eq_u32_e64 s[26:27], 0, v186
	v_and_b32_e32 v186, v245, v215
	v_cmp_eq_u32_e64 s[28:29], 0, v186
	v_and_b32_e32 v186, v245, v216
	v_cmp_eq_u32_e64 s[30:31], 0, v186
	v_and_b32_e32 v186, v245, v217
	v_cmp_eq_u32_e64 s[34:35], 0, v186
	v_and_b32_e32 v186, v245, v218
	v_cmp_eq_u32_e64 s[36:37], 0, v186
	v_and_b32_e32 v186, v246, v203
	v_cmp_eq_u32_e64 s[38:39], 0, v186
	v_cndmask_b32_e64 v114, v114, v238, s[0:1]
	v_cndmask_b32_e64 v115, v115, v238, s[70:71]
	v_cndmask_b32_e64 v186, v98, v238, s[38:39]
	v_and_b32_e32 v98, v246, v204
	v_cmp_eq_u32_e64 s[40:41], 0, v98
	v_and_b32_e32 v98, v246, v205
	v_cmp_eq_u32_e64 s[42:43], 0, v98
	v_and_b32_e32 v98, v246, v206
	v_cmp_eq_u32_e64 s[44:45], 0, v98
	v_and_b32_e32 v98, v246, v207
	v_cmp_eq_u32_e64 s[46:47], 0, v98
	v_and_b32_e32 v98, v246, v208
	v_cmp_eq_u32_e64 s[48:49], 0, v98
	v_and_b32_e32 v98, v246, v209
	v_cmp_eq_u32_e64 s[50:51], 0, v98
	v_and_b32_e32 v98, v246, v210
	v_cmp_eq_u32_e64 s[52:53], 0, v98
	v_and_b32_e32 v98, v246, v211
	v_cmp_eq_u32_e64 s[54:55], 0, v98
	v_and_b32_e32 v98, v246, v212
	v_cmp_eq_u32_e64 s[56:57], 0, v98
	v_and_b32_e32 v98, v246, v213
	v_cmp_eq_u32_e64 s[58:59], 0, v98
	v_and_b32_e32 v98, v246, v214
	v_cmp_eq_u32_e64 s[60:61], 0, v98
	v_and_b32_e32 v98, v246, v215
	v_cmp_eq_u32_e64 s[62:63], 0, v98
	v_and_b32_e32 v98, v246, v216
	v_cmp_eq_u32_e64 s[64:65], 0, v98
	v_and_b32_e32 v98, v246, v217
	v_cmp_eq_u32_e64 s[66:67], 0, v98
	v_and_b32_e32 v98, v246, v218
	v_cndmask_b32_e64 v187, v99, v238, s[40:41]
	v_cmp_eq_u32_e64 s[68:69], 0, v98
	v_max_f32_e32 v98, v115, v115
	v_max_f32_e32 v99, v114, v114
	v_cndmask_b32_e64 v116, v116, v238, s[8:9]
	v_cndmask_b32_e64 v117, v117, v238, s[10:11]
	v_max_f32_e32 v98, v99, v98
	v_cndmask_b32_e64 v118, v118, v238, s[12:13]
	v_cndmask_b32_e64 v119, v119, v238, s[14:15]
	v_max3_f32 v98, v98, v116, v117
	v_cndmask_b32_e64 v120, v120, v238, s[16:17]
	v_cndmask_b32_e64 v121, v121, v238, s[18:19]
	v_max3_f32 v98, v98, v118, v119
	v_cndmask_b32_e64 v122, v122, v238, s[20:21]
	v_cndmask_b32_e64 v123, v123, v238, s[22:23]
	v_max3_f32 v98, v98, v120, v121
	v_cndmask_b32_e64 v124, v124, v238, s[24:25]
	v_cndmask_b32_e64 v125, v125, v238, s[26:27]
	v_max3_f32 v98, v98, v122, v123
	v_cndmask_b32_e64 v126, v126, v238, s[28:29]
	v_cndmask_b32_e64 v127, v127, v238, s[30:31]
	v_max3_f32 v98, v98, v124, v125
	v_cndmask_b32_e64 v128, v128, v238, s[34:35]
	v_cndmask_b32_e64 v129, v129, v238, s[36:37]
	v_max3_f32 v98, v98, v126, v127
	v_max3_f32 v98, v98, v128, v129
	v_cndmask_b32_e64 v188, v100, v238, s[42:43]
	v_cndmask_b32_e64 v189, v101, v238, s[44:45]
	v_max3_f32 v98, v98, v186, v187
	v_cndmask_b32_e64 v190, v102, v238, s[46:47]
	v_cndmask_b32_e64 v191, v103, v238, s[48:49]
	v_max3_f32 v98, v98, v188, v189
	v_cndmask_b32_e64 v192, v104, v238, s[50:51]
	v_cndmask_b32_e64 v193, v105, v238, s[52:53]
	v_max3_f32 v98, v98, v190, v191
	v_cndmask_b32_e64 v194, v106, v238, s[54:55]
	v_cndmask_b32_e64 v195, v107, v238, s[56:57]
	v_max3_f32 v98, v98, v192, v193
	v_cndmask_b32_e64 v196, v108, v238, s[58:59]
	v_cndmask_b32_e64 v197, v109, v238, s[60:61]
	v_max3_f32 v98, v98, v194, v195
	v_cndmask_b32_e64 v198, v110, v238, s[62:63]
	v_cndmask_b32_e64 v199, v111, v238, s[64:65]
	v_max3_f32 v98, v98, v196, v197
	v_cndmask_b32_e64 v200, v112, v238, s[66:67]
	v_cndmask_b32_e64 v201, v113, v238, s[68:69]
	v_max3_f32 v98, v98, v198, v199
	v_max3_f32 v98, v98, v200, v201
	v_mov_b32_e32 v99, v98
	s_nop 1
	v_permlane32_swap_b32 v99, v98
	s_waitcnt lgkmcnt(0)
	v_max_f32_e32 v99, v99, v99
	v_max_f32_e32 v98, v98, v99
	v_cmp_lt_f32_e32 vcc, 0, v98
	s_cbranch_vccz .LBB0_3903
; template <int DQK, int DV, int MODE, bool QNORM, int SK, int NQ> ...
;     ...
;                 if (__ballot(tm > 0.f) != 0ull) {
;                     const float dl = fmaxf(tm, 0.f); m_run[qh] += dl;
;                     const float alpha = __builtin_amdgcn_exp2f(-dl);
;                     l_run[qh] *= alpha;
; #pragma unroll
;                     for (int sub = 0; sub < NSUB; ++sub)
; #pragma unroll
;                         for (int r = 0; r < 16; ++r) sc[qh][sub][r] -= dl;
; #pragma unroll
;                     for (int dt = 0; dt < DV / 32; ++dt)
; #pragma unroll
;                         for (int r = 0; r < 16; ++r) o[qh][dt][r] *= alpha;
;                 }
	v_max_f32_e32 v98, v98, v98
	v_max_f32_e32 v98, 0, v98
	v_exp_f32_e64 v100, -v98
	v_add_f32_e32 v247, v247, v98
	v_pk_add_f32 v[114:115], v[114:115], v[98:99] op_sel_hi:[1,0] neg_lo:[0,1] neg_hi:[0,1]
	v_pk_add_f32 v[116:117], v[116:117], v[98:99] op_sel_hi:[1,0] neg_lo:[0,1] neg_hi:[0,1]
	v_mul_f32_e32 v183, v183, v100
	v_pk_add_f32 v[118:119], v[118:119], v[98:99] op_sel_hi:[1,0] neg_lo:[0,1] neg_hi:[0,1]
	v_pk_add_f32 v[120:121], v[120:121], v[98:99] op_sel_hi:[1,0] neg_lo:[0,1] neg_hi:[0,1]
	v_pk_add_f32 v[122:123], v[122:123], v[98:99] op_sel_hi:[1,0] neg_lo:[0,1] neg_hi:[0,1]
	v_pk_add_f32 v[124:125], v[124:125], v[98:99] op_sel_hi:[1,0] neg_lo:[0,1] neg_hi:[0,1]
	v_pk_add_f32 v[126:127], v[126:127], v[98:99] op_sel_hi:[1,0] neg_lo:[0,1] neg_hi:[0,1]
	v_pk_add_f32 v[128:129], v[128:129], v[98:99] op_sel_hi:[1,0] neg_lo:[0,1] neg_hi:[0,1]
	v_pk_add_f32 v[186:187], v[186:187], v[98:99] op_sel_hi:[1,0] neg_lo:[0,1] neg_hi:[0,1]
	v_pk_add_f32 v[188:189], v[188:189], v[98:99] op_sel_hi:[1,0] neg_lo:[0,1] neg_hi:[0,1]
	v_pk_add_f32 v[190:191], v[190:191], v[98:99] op_sel_hi:[1,0] neg_lo:[0,1] neg_hi:[0,1]
	v_pk_add_f32 v[192:193], v[192:193], v[98:99] op_sel_hi:[1,0] neg_lo:[0,1] neg_hi:[0,1]
	v_pk_add_f32 v[194:195], v[194:195], v[98:99] op_sel_hi:[1,0] neg_lo:[0,1] neg_hi:[0,1]
	v_pk_add_f32 v[196:197], v[196:197], v[98:99] op_sel_hi:[1,0] neg_lo:[0,1] neg_hi:[0,1]
	v_pk_add_f32 v[198:199], v[198:199], v[98:99] op_sel_hi:[1,0] neg_lo:[0,1] neg_hi:[0,1]
	v_pk_add_f32 v[200:201], v[200:201], v[98:99] op_sel_hi:[1,0] neg_lo:[0,1] neg_hi:[0,1]
	v_pk_mul_f32 v[64:65], v[64:65], v[100:101] op_sel_hi:[1,0]
	v_pk_mul_f32 v[62:63], v[62:63], v[100:101] op_sel_hi:[1,0]
	v_pk_mul_f32 v[60:61], v[60:61], v[100:101] op_sel_hi:[1,0]
	v_pk_mul_f32 v[58:59], v[58:59], v[100:101] op_sel_hi:[1,0]
	v_pk_mul_f32 v[56:57], v[56:57], v[100:101] op_sel_hi:[1,0]
	v_pk_mul_f32 v[54:55], v[54:55], v[100:101] op_sel_hi:[1,0]
	v_pk_mul_f32 v[52:53], v[52:53], v[100:101] op_sel_hi:[1,0]
	v_pk_mul_f32 v[50:51], v[50:51], v[100:101] op_sel_hi:[1,0]
	v_pk_mul_f32 v[48:49], v[48:49], v[100:101] op_sel_hi:[1,0]
	v_pk_mul_f32 v[46:47], v[46:47], v[100:101] op_sel_hi:[1,0]
	v_pk_mul_f32 v[44:45], v[44:45], v[100:101] op_sel_hi:[1,0]
	v_pk_mul_f32 v[42:43], v[42:43], v[100:101] op_sel_hi:[1,0]
	v_pk_mul_f32 v[40:41], v[40:41], v[100:101] op_sel_hi:[1,0]
	v_pk_mul_f32 v[38:39], v[38:39], v[100:101] op_sel_hi:[1,0]
	v_pk_mul_f32 v[36:37], v[36:37], v[100:101] op_sel_hi:[1,0]
	v_pk_mul_f32 v[34:35], v[34:35], v[100:101] op_sel_hi:[1,0]

; template <int DQK, int DV, int MODE, bool QNORM, int SK, int NQ> ...
;     ...
;             for (int qh = 0; qh < NQ; ++qh) {
;                 float tm = sc[qh][0][0];
; #pragma unroll
;                 for (int sub = 0; sub < NSUB; ++sub)
; #pragma unroll
;                     for (int r = 0; r < 16; ++r) tm = fmaxf(tm, sc[qh][sub][r]);
;                 tm = fmaxf(tm, __shfl_xor(tm, 32));
;                 if (__ballot(tm > 0.f) != 0ull) {
;                     const float dl = fmaxf(tm, 0.f); m_run[qh] += dl;
;                     const float alpha = __builtin_amdgcn_exp2f(-dl);
;                     l_run[qh] *= alpha;
; #pragma unroll
;                     for (int sub = 0; sub < NSUB; ++sub)
; #pragma unroll
;                         for (int r = 0; r < 16; ++r) sc[qh][sub][r] -= dl;
; #pragma unroll
;                     for (int dt = 0; dt < DV / 32; ++dt)
; #pragma unroll
;                         for (int r = 0; r < 16; ++r) o[qh][dt][r] *= alpha;
;                 }
.LBB0_4309:
	s_nop 1
	v_max_f32_e32 v143, v51, v51
	v_max_f32_e32 v145, v50, v50
	v_max_f32_e32 v143, v145, v143
	v_max3_f32 v143, v143, v52, v53
	v_max3_f32 v143, v143, v54, v55
	v_max3_f32 v143, v143, v56, v57
	v_max3_f32 v143, v143, v58, v59
	v_max3_f32 v143, v143, v60, v61
	v_max3_f32 v143, v143, v62, v63
	v_max3_f32 v143, v143, v64, v65
	v_max3_f32 v143, v143, v34, v35
	v_max3_f32 v143, v143, v36, v37
	v_max3_f32 v143, v143, v38, v39
	v_max3_f32 v143, v143, v40, v41
	v_max3_f32 v143, v143, v42, v43
	v_max3_f32 v143, v143, v44, v45
	v_max3_f32 v143, v143, v46, v47
	v_max3_f32 v143, v143, v48, v49
	v_mov_b32_e32 v145, v143
	s_nop 1
	v_permlane32_swap_b32 v145, v143
	s_waitcnt lgkmcnt(0)
	v_max_f32_e32 v145, v145, v145
	v_max_f32_e32 v143, v143, v145
	v_cmp_lt_f32_e32 vcc, 0, v143
	s_cbranch_vccz .LBB0_4311
	v_max_f32_e32 v143, v143, v143
	v_max_f32_e32 v160, 0, v143
	v_exp_f32_e64 v162, -v160
	v_pk_add_f32 v[50:51], v[50:51], v[160:161] op_sel_hi:[1,0] neg_lo:[0,1] neg_hi:[0,1]
	v_pk_add_f32 v[52:53], v[52:53], v[160:161] op_sel_hi:[1,0] neg_lo:[0,1] neg_hi:[0,1]
	v_pk_add_f32 v[54:55], v[54:55], v[160:161] op_sel_hi:[1,0] neg_lo:[0,1] neg_hi:[0,1]
	v_pk_add_f32 v[56:57], v[56:57], v[160:161] op_sel_hi:[1,0] neg_lo:[0,1] neg_hi:[0,1]
	v_pk_add_f32 v[58:59], v[58:59], v[160:161] op_sel_hi:[1,0] neg_lo:[0,1] neg_hi:[0,1]
	v_pk_add_f32 v[60:61], v[60:61], v[160:161] op_sel_hi:[1,0] neg_lo:[0,1] neg_hi:[0,1]
	v_pk_add_f32 v[62:63], v[62:63], v[160:161] op_sel_hi:[1,0] neg_lo:[0,1] neg_hi:[0,1]
	v_pk_add_f32 v[64:65], v[64:65], v[160:161] op_sel_hi:[1,0] neg_lo:[0,1] neg_hi:[0,1]
	v_pk_add_f32 v[34:35], v[34:35], v[160:161] op_sel_hi:[1,0] neg_lo:[0,1] neg_hi:[0,1]
	v_pk_add_f32 v[36:37], v[36:37], v[160:161] op_sel_hi:[1,0] neg_lo:[0,1] neg_hi:[0,1]
	v_pk_add_f32 v[38:39], v[38:39], v[160:161] op_sel_hi:[1,0] neg_lo:[0,1] neg_hi:[0,1]
	v_pk_add_f32 v[40:41], v[40:41], v[160:161] op_sel_hi:[1,0] neg_lo:[0,1] neg_hi:[0,1]
	v_pk_add_f32 v[42:43], v[42:43], v[160:161] op_sel_hi:[1,0] neg_lo:[0,1] neg_hi:[0,1]
	v_pk_add_f32 v[44:45], v[44:45], v[160:161] op_sel_hi:[1,0] neg_lo:[0,1] neg_hi:[0,1]
	v_pk_add_f32 v[46:47], v[46:47], v[160:161] op_sel_hi:[1,0] neg_lo:[0,1] neg_hi:[0,1]
	v_pk_add_f32 v[48:49], v[48:49], v[160:161] op_sel_hi:[1,0] neg_lo:[0,1] neg_hi:[0,1]
	v_add_f32_e32 v1, v1, v160
	v_pk_mul_f32 v[32:33], v[32:33], v[162:163] op_sel_hi:[1,0]
	v_pk_mul_f32 v[30:31], v[30:31], v[162:163] op_sel_hi:[1,0]
	v_pk_mul_f32 v[28:29], v[28:29], v[162:163] op_sel_hi:[1,0]
	v_pk_mul_f32 v[26:27], v[26:27], v[162:163] op_sel_hi:[1,0]
	v_pk_mul_f32 v[24:25], v[24:25], v[162:163] op_sel_hi:[1,0]
	v_pk_mul_f32 v[22:23], v[22:23], v[162:163] op_sel_hi:[1,0]
	v_pk_mul_f32 v[20:21], v[20:21], v[162:163] op_sel_hi:[1,0]
	v_pk_mul_f32 v[18:19], v[18:19], v[162:163] op_sel_hi:[1,0]
	v_pk_mul_f32 v[16:17], v[16:17], v[162:163] op_sel_hi:[1,0]
	v_pk_mul_f32 v[14:15], v[14:15], v[162:163] op_sel_hi:[1,0]
	v_pk_mul_f32 v[12:13], v[12:13], v[162:163] op_sel_hi:[1,0]
	v_pk_mul_f32 v[10:11], v[10:11], v[162:163] op_sel_hi:[1,0]
	v_pk_mul_f32 v[8:9], v[8:9], v[162:163] op_sel_hi:[1,0]
	v_pk_mul_f32 v[6:7], v[6:7], v[162:163] op_sel_hi:[1,0]
	v_pk_mul_f32 v[4:5], v[4:5], v[162:163] op_sel_hi:[1,0]
	v_pk_mul_f32 v[2:3], v[2:3], v[162:163] op_sel_hi:[1,0]
	v_mul_f32_e32 v115, v115, v162

; template <int DQK, int DV, int MODE, bool QNORM, int SK, int NQ> ...
;     ...
;             for (int qh = 0; qh < NQ; ++qh) {
;                 float tm = sc[qh][0][0];
; #pragma unroll
;                 for (int sub = 0; sub < NSUB; ++sub)
; #pragma unroll
;                     for (int r = 0; r < 16; ++r) tm = fmaxf(tm, sc[qh][sub][r]);
;                 tm = fmaxf(tm, __shfl_xor(tm, 32));
;                 if (__ballot(tm > 0.f) != 0ull) {
;                     const float dl = fmaxf(tm, 0.f); m_run[qh] += dl;
;                     const float alpha = __builtin_amdgcn_exp2f(-dl);
;                     l_run[qh] *= alpha;
; #pragma unroll
;                     for (int sub = 0; sub < NSUB; ++sub)
; #pragma unroll
;                         for (int r = 0; r < 16; ++r) sc[qh][sub][r] -= dl;
; #pragma unroll
;                     for (int dt = 0; dt < DV / 32; ++dt)
; #pragma unroll
;                         for (int r = 0; r < 16; ++r) o[qh][dt][r] *= alpha;
;                 }
.LBB0_4327:
	s_nop 1
	v_max_f32_e32 v1, v51, v51
	v_max_f32_e32 v66, v50, v50
	v_max_f32_e32 v1, v66, v1
	v_max3_f32 v1, v1, v52, v53
	v_max3_f32 v1, v1, v54, v55
	v_max3_f32 v1, v1, v56, v57
	v_max3_f32 v1, v1, v58, v59
	v_max3_f32 v1, v1, v60, v61
	v_max3_f32 v1, v1, v62, v63
	v_max3_f32 v1, v1, v64, v65
	v_max3_f32 v1, v1, v34, v35
	v_max3_f32 v1, v1, v36, v37
	v_max3_f32 v1, v1, v38, v39
	v_max3_f32 v1, v1, v40, v41
	v_max3_f32 v1, v1, v42, v43
	v_max3_f32 v1, v1, v44, v45
	v_max3_f32 v1, v1, v46, v47
	v_max3_f32 v1, v1, v48, v49
	v_mov_b32_e32 v66, v1
	s_nop 1
	v_permlane32_swap_b32 v66, v1
	s_waitcnt lgkmcnt(0)
	v_max_f32_e32 v66, v66, v66
	v_max_f32_e32 v1, v1, v66
	v_cmp_lt_f32_e32 vcc, 0, v1
	s_cbranch_vccz .LBB0_4286
	v_max_f32_e32 v1, v1, v1
	v_max_f32_e32 v66, 0, v1
	v_exp_f32_e64 v68, -v66
	v_pk_add_f32 v[50:51], v[50:51], v[66:67] op_sel_hi:[1,0] neg_lo:[0,1] neg_hi:[0,1]
	v_pk_add_f32 v[52:53], v[52:53], v[66:67] op_sel_hi:[1,0] neg_lo:[0,1] neg_hi:[0,1]
	v_pk_add_f32 v[54:55], v[54:55], v[66:67] op_sel_hi:[1,0] neg_lo:[0,1] neg_hi:[0,1]
	v_pk_add_f32 v[56:57], v[56:57], v[66:67] op_sel_hi:[1,0] neg_lo:[0,1] neg_hi:[0,1]
	v_pk_add_f32 v[58:59], v[58:59], v[66:67] op_sel_hi:[1,0] neg_lo:[0,1] neg_hi:[0,1]
	v_pk_add_f32 v[60:61], v[60:61], v[66:67] op_sel_hi:[1,0] neg_lo:[0,1] neg_hi:[0,1]
	v_pk_add_f32 v[62:63], v[62:63], v[66:67] op_sel_hi:[1,0] neg_lo:[0,1] neg_hi:[0,1]
	v_pk_add_f32 v[64:65], v[64:65], v[66:67] op_sel_hi:[1,0] neg_lo:[0,1] neg_hi:[0,1]
	v_pk_add_f32 v[34:35], v[34:35], v[66:67] op_sel_hi:[1,0] neg_lo:[0,1] neg_hi:[0,1]
	v_pk_add_f32 v[36:37], v[36:37], v[66:67] op_sel_hi:[1,0] neg_lo:[0,1] neg_hi:[0,1]
	v_pk_add_f32 v[38:39], v[38:39], v[66:67] op_sel_hi:[1,0] neg_lo:[0,1] neg_hi:[0,1]
	v_pk_add_f32 v[40:41], v[40:41], v[66:67] op_sel_hi:[1,0] neg_lo:[0,1] neg_hi:[0,1]
	v_pk_add_f32 v[42:43], v[42:43], v[66:67] op_sel_hi:[1,0] neg_lo:[0,1] neg_hi:[0,1]
	v_pk_add_f32 v[44:45], v[44:45], v[66:67] op_sel_hi:[1,0] neg_lo:[0,1] neg_hi:[0,1]
	v_pk_add_f32 v[46:47], v[46:47], v[66:67] op_sel_hi:[1,0] neg_lo:[0,1] neg_hi:[0,1]
	v_pk_add_f32 v[48:49], v[48:49], v[66:67] op_sel_hi:[1,0] neg_lo:[0,1] neg_hi:[0,1]
	v_pk_mul_f32 v[32:33], v[32:33], v[68:69] op_sel_hi:[1,0]
	v_pk_mul_f32 v[30:31], v[30:31], v[68:69] op_sel_hi:[1,0]
	v_pk_mul_f32 v[28:29], v[28:29], v[68:69] op_sel_hi:[1,0]
	v_pk_mul_f32 v[26:27], v[26:27], v[68:69] op_sel_hi:[1,0]
	v_pk_mul_f32 v[24:25], v[24:25], v[68:69] op_sel_hi:[1,0]
	v_pk_mul_f32 v[22:23], v[22:23], v[68:69] op_sel_hi:[1,0]
	v_pk_mul_f32 v[20:21], v[20:21], v[68:69] op_sel_hi:[1,0]
	v_pk_mul_f32 v[18:19], v[18:19], v[68:69] op_sel_hi:[1,0]
	v_pk_mul_f32 v[16:17], v[16:17], v[68:69] op_sel_hi:[1,0]
	v_pk_mul_f32 v[14:15], v[14:15], v[68:69] op_sel_hi:[1,0]
	v_pk_mul_f32 v[12:13], v[12:13], v[68:69] op_sel_hi:[1,0]
	v_pk_mul_f32 v[10:11], v[10:11], v[68:69] op_sel_hi:[1,0]
	v_pk_mul_f32 v[8:9], v[8:9], v[68:69] op_sel_hi:[1,0]
	v_pk_mul_f32 v[6:7], v[6:7], v[68:69] op_sel_hi:[1,0]
	v_pk_mul_f32 v[4:5], v[4:5], v[68:69] op_sel_hi:[1,0]
	v_pk_mul_f32 v[2:3], v[2:3], v[68:69] op_sel_hi:[1,0]
	v_mul_f32_e32 v115, v115, v68
	s_branch .LBB0_4286

; template <int DQK, int DV, int MODE, bool QNORM, bool PF> ...
;     ...
;         float tm = s[0];
; #pragma unroll
;         for (int r = 1; r < 16; ++r) tm = fmaxf(tm, s[r]);
;         tm = fmaxf(tm, __shfl_xor(tm, 32));
;         if (__ballot(tm > 0.f) != 0ull) {
;             const float dl = fmaxf(tm, 0.f); m_run += dl;
;             const float alpha = __builtin_amdgcn_exp2f(-dl);
;             l_run *= alpha;
; #pragma unroll
;             for (int r = 0; r < 16; ++r) s[r] -= dl;
; #pragma unroll
;             for (int dt = 0; dt < DV / 32; ++dt)
; #pragma unroll
;                 for (int r = 0; r < 16; ++r) o[dt][r] *= alpha;
;         }
.LBB0_4345:
	v_max_f32_e32 v114, v35, v35
	v_max_f32_e32 v115, v34, v34
	v_max_f32_e32 v114, v115, v114
	v_max3_f32 v114, v114, v36, v37
	v_max3_f32 v114, v114, v38, v39
	v_max3_f32 v114, v114, v40, v41
	v_max3_f32 v114, v114, v42, v43
	v_max3_f32 v114, v114, v44, v45
	v_max3_f32 v114, v114, v46, v47
	v_max3_f32 v114, v114, v48, v49
	v_mov_b32_e32 v115, v114
	s_nop 1
	v_permlane32_swap_b32 v115, v114
	s_waitcnt lgkmcnt(0)
	v_max_f32_e32 v115, v115, v115
	v_max_f32_e32 v114, v114, v115
	v_cmp_lt_f32_e32 vcc, 0, v114
	s_cbranch_vccz .LBB0_4347
	v_max_f32_e32 v114, v114, v114
	v_max_f32_e32 v114, 0, v114
	v_exp_f32_e64 v116, -v114
	v_pk_add_f32 v[34:35], v[34:35], v[114:115] op_sel_hi:[1,0] neg_lo:[0,1] neg_hi:[0,1]
	v_pk_add_f32 v[36:37], v[36:37], v[114:115] op_sel_hi:[1,0] neg_lo:[0,1] neg_hi:[0,1]
	v_pk_add_f32 v[38:39], v[38:39], v[114:115] op_sel_hi:[1,0] neg_lo:[0,1] neg_hi:[0,1]
	v_pk_add_f32 v[40:41], v[40:41], v[114:115] op_sel_hi:[1,0] neg_lo:[0,1] neg_hi:[0,1]
	v_pk_add_f32 v[42:43], v[42:43], v[114:115] op_sel_hi:[1,0] neg_lo:[0,1] neg_hi:[0,1]
	v_pk_add_f32 v[44:45], v[44:45], v[114:115] op_sel_hi:[1,0] neg_lo:[0,1] neg_hi:[0,1]
	v_pk_add_f32 v[46:47], v[46:47], v[114:115] op_sel_hi:[1,0] neg_lo:[0,1] neg_hi:[0,1]
	v_pk_add_f32 v[48:49], v[48:49], v[114:115] op_sel_hi:[1,0] neg_lo:[0,1] neg_hi:[0,1]
	v_add_f32_e32 v1, v1, v114
	v_pk_mul_f32 v[32:33], v[32:33], v[116:117] op_sel_hi:[1,0]
	v_pk_mul_f32 v[30:31], v[30:31], v[116:117] op_sel_hi:[1,0]
	v_pk_mul_f32 v[28:29], v[28:29], v[116:117] op_sel_hi:[1,0]
	v_pk_mul_f32 v[26:27], v[26:27], v[116:117] op_sel_hi:[1,0]
	v_pk_mul_f32 v[24:25], v[24:25], v[116:117] op_sel_hi:[1,0]
	v_pk_mul_f32 v[22:23], v[22:23], v[116:117] op_sel_hi:[1,0]
	v_pk_mul_f32 v[20:21], v[20:21], v[116:117] op_sel_hi:[1,0]
	v_pk_mul_f32 v[18:19], v[18:19], v[116:117] op_sel_hi:[1,0]
	v_pk_mul_f32 v[16:17], v[16:17], v[116:117] op_sel_hi:[1,0]
	v_pk_mul_f32 v[14:15], v[14:15], v[116:117] op_sel_hi:[1,0]
	v_pk_mul_f32 v[12:13], v[12:13], v[116:117] op_sel_hi:[1,0]
	v_pk_mul_f32 v[10:11], v[10:11], v[116:117] op_sel_hi:[1,0]
	v_pk_mul_f32 v[8:9], v[8:9], v[116:117] op_sel_hi:[1,0]
	v_pk_mul_f32 v[6:7], v[6:7], v[116:117] op_sel_hi:[1,0]
	v_pk_mul_f32 v[4:5], v[4:5], v[116:117] op_sel_hi:[1,0]
	v_pk_mul_f32 v[2:3], v[2:3], v[116:117] op_sel_hi:[1,0]
	v_mul_f32_e32 v141, v141, v116

; #define LAS __attribute__((address_space(3)))
;     __device__ __forceinline__ static float sg(float g, float uu) { return g * __builtin_amdgcn_rcpf(1.0f + __builtin_amdgcn_exp2f(-1.4426950408889634f * g)) * uu; }
; template <int DQK, int DV, int MODE, bool QNORM, int SK, int NQ> ...
;     ...
;             __builtin_amdgcn_s_setprio(1);
; #pragma unroll
;             for (int d0 = 0; d0 < DQK / 16; ++d0)
; #pragma unroll
;                 for (int sub = 0; sub < NSUB; ++sub) {
;                     const bf16x8 kf = *(const LAS bf16x8*)(sb + (sub * 32 + r32) * KP + hi * 16 + d0 * 32);
; #pragma unroll
;                     for (int qh = 0; qh < NQ; ++qh) sc[qh][sub] = __builtin_amdgcn_mfma_f32_32x32x16_bf16(kf, qf[qh][d0], sc[qh][sub], 0, 0, 0);
;                 }
;             }
;             __builtin_amdgcn_s_setprio(0);
; #pragma unroll
;             for (int sub = 0; sub < NSUB; ++sub) {
;                 const int st = NSUB * sg + sub;
;                 if (QNORM) {
; #pragma unroll
;                     for (int qh = 0; qh < NQ; ++qh)
; #pragma unroll
;                         for (int r = 0; r < 16; ++r) sc[qh][sub][r] = sc[qh][sub][r] * sscale[qh] - m_run[qh];
;     ...
;             for (int qh = 0; qh < NQ; ++qh) {
;                 float tm = sc[qh][0][0];
; #pragma unroll
;                 for (int sub = 0; sub < NSUB; ++sub)
; #pragma unroll
;                     for (int r = 0; r < 16; ++r) tm = fmaxf(tm, sc[qh][sub][r]);
;                 tm = fmaxf(tm, __shfl_xor(tm, 32));
;                 if (__ballot(tm > 0.f) != 0ull) {
;                     const float dl = fmaxf(tm, 0.f); m_run[qh] += dl;
;                     const float alpha = __builtin_amdgcn_exp2f(-dl);
;                     l_run[qh] *= alpha;
; #pragma unroll
;                     for (int sub = 0; sub < NSUB; ++sub)
; #pragma unroll
;                         for (int r = 0; r < 16; ++r) sc[qh][sub][r] -= dl;
; #pragma unroll
;                     for (int dt = 0; dt < DV / 32; ++dt)
; #pragma unroll
;                         for (int r = 0; r < 16; ++r) o[qh][dt][r] *= alpha;
;                 }
.LBB0_4653:
	s_or_b64 exec, exec, s[12:13]
	s_bitcmp1_b32 s15, 0
	s_cselect_b32 s12, 0x6a00, 0
	s_add_i32 s12, s12, 0
	s_setprio 1
	v_add3_u32 v1, s12, v180, v181
	ds_read_b128 v[66:69], v1
	ds_read_b128 v[192:195], v1 offset:32
	s_waitcnt lgkmcnt(1)
	v_mfma_f32_32x32x16_bf16 v[66:81], v[66:69], v[142:145], 0
	s_waitcnt lgkmcnt(0)
	v_mfma_f32_32x32x16_bf16 v[66:81], v[192:195], v[138:141], v[66:81]
	ds_read_b128 v[192:195], v1 offset:64
	s_waitcnt lgkmcnt(0)
	v_mfma_f32_32x32x16_bf16 v[66:81], v[192:195], v[134:137], v[66:81]
	ds_read_b128 v[192:195], v1 offset:96
	s_waitcnt lgkmcnt(0)
	v_mfma_f32_32x32x16_bf16 v[66:81], v[192:195], v[126:129], v[66:81]
	ds_read_b128 v[192:195], v1 offset:128
	s_waitcnt lgkmcnt(0)
	v_mfma_f32_32x32x16_bf16 v[66:81], v[192:195], v[118:121], v[66:81]
	ds_read_b128 v[192:195], v1 offset:160
	s_waitcnt lgkmcnt(0)
	v_mfma_f32_32x32x16_bf16 v[66:81], v[192:195], v[110:113], v[66:81]
	ds_read_b128 v[192:195], v1 offset:192
	s_waitcnt lgkmcnt(0)
	v_mfma_f32_32x32x16_bf16 v[66:81], v[192:195], v[102:105], v[66:81]
	ds_read_b128 v[192:195], v1 offset:224
	s_waitcnt lgkmcnt(0)
	v_mfma_f32_32x32x16_bf16 v[66:81], v[192:195], v[130:133], v[66:81]
	ds_read_b128 v[192:195], v1 offset:256
	s_waitcnt lgkmcnt(0)
	v_mfma_f32_32x32x16_bf16 v[66:81], v[192:195], v[122:125], v[66:81]
	ds_read_b128 v[192:195], v1 offset:288
	s_waitcnt lgkmcnt(0)
	v_mfma_f32_32x32x16_bf16 v[66:81], v[192:195], v[114:117], v[66:81]
	ds_read_b128 v[192:195], v1 offset:320
	s_waitcnt lgkmcnt(0)
	v_mfma_f32_32x32x16_bf16 v[66:81], v[192:195], v[106:109], v[66:81]
	ds_read_b128 v[192:195], v1 offset:352
	s_waitcnt lgkmcnt(0)
	v_mfma_f32_32x32x16_bf16 v[66:81], v[192:195], v[98:101], v[66:81]
	ds_read_b128 v[192:195], v1 offset:384
	s_waitcnt lgkmcnt(0)
	v_mfma_f32_32x32x16_bf16 v[66:81], v[192:195], v[94:97], v[66:81]
	ds_read_b128 v[192:195], v1 offset:416
	s_waitcnt lgkmcnt(0)
	v_mfma_f32_32x32x16_bf16 v[66:81], v[192:195], v[90:93], v[66:81]
	ds_read_b128 v[192:195], v1 offset:448
	s_waitcnt lgkmcnt(0)
	v_mfma_f32_32x32x16_bf16 v[66:81], v[192:195], v[86:89], v[66:81]
	ds_read_b128 v[192:195], v1 offset:480
	s_waitcnt lgkmcnt(0)
	v_mfma_f32_32x32x16_bf16 v[66:81], v[192:195], v[82:85], v[66:81]
	s_setprio 0
	s_nop 10
	v_pk_fma_f32 v[66:67], v[170:171], v[66:67], v[172:173] op_sel_hi:[1,1,0] neg_lo:[0,0,1] neg_hi:[0,0,1]
	v_pk_fma_f32 v[68:69], v[170:171], v[68:69], v[172:173] op_sel_hi:[1,1,0] neg_lo:[0,0,1] neg_hi:[0,0,1]
	v_max_f32_e32 v1, v66, v67
	v_pk_fma_f32 v[70:71], v[170:171], v[70:71], v[172:173] op_sel_hi:[1,1,0] neg_lo:[0,0,1] neg_hi:[0,0,1]
	v_max3_f32 v1, v1, v68, v69
	v_pk_fma_f32 v[72:73], v[170:171], v[72:73], v[172:173] op_sel_hi:[1,1,0] neg_lo:[0,0,1] neg_hi:[0,0,1]
	v_max3_f32 v1, v1, v70, v71
	v_pk_fma_f32 v[74:75], v[170:171], v[74:75], v[172:173] op_sel_hi:[1,1,0] neg_lo:[0,0,1] neg_hi:[0,0,1]
	v_max3_f32 v1, v1, v72, v73
	v_pk_fma_f32 v[76:77], v[170:171], v[76:77], v[172:173] op_sel_hi:[1,1,0] neg_lo:[0,0,1] neg_hi:[0,0,1]
	v_max3_f32 v1, v1, v74, v75
	v_pk_fma_f32 v[78:79], v[170:171], v[78:79], v[172:173] op_sel_hi:[1,1,0] neg_lo:[0,0,1] neg_hi:[0,0,1]
	v_max3_f32 v1, v1, v76, v77
	v_pk_fma_f32 v[80:81], v[170:171], v[80:81], v[172:173] op_sel_hi:[1,1,0] neg_lo:[0,0,1] neg_hi:[0,0,1]
	v_max3_f32 v1, v1, v78, v79
	v_max3_f32 v1, v1, v80, v81
	v_mov_b32_e32 v167, v1
	s_nop 1
	v_permlane32_swap_b32 v167, v1
	s_waitcnt lgkmcnt(0)
	v_max_f32_e32 v167, v167, v167
	v_max_f32_e32 v1, v1, v167
	v_cmp_lt_f32_e32 vcc, 0, v1
	s_cbranch_vccz .LBB0_4655
	v_max_f32_e32 v1, v1, v1
	v_max_f32_e32 v192, 0, v1
	v_exp_f32_e64 v194, -v192
	v_pk_add_f32 v[66:67], v[66:67], v[192:193] op_sel_hi:[1,0] neg_lo:[0,1] neg_hi:[0,1]
	v_pk_add_f32 v[68:69], v[68:69], v[192:193] op_sel_hi:[1,0] neg_lo:[0,1] neg_hi:[0,1]
	v_pk_add_f32 v[70:71], v[70:71], v[192:193] op_sel_hi:[1,0] neg_lo:[0,1] neg_hi:[0,1]
	v_pk_add_f32 v[72:73], v[72:73], v[192:193] op_sel_hi:[1,0] neg_lo:[0,1] neg_hi:[0,1]
	v_pk_add_f32 v[74:75], v[74:75], v[192:193] op_sel_hi:[1,0] neg_lo:[0,1] neg_hi:[0,1]
	v_pk_add_f32 v[76:77], v[76:77], v[192:193] op_sel_hi:[1,0] neg_lo:[0,1] neg_hi:[0,1]
	v_pk_add_f32 v[78:79], v[78:79], v[192:193] op_sel_hi:[1,0] neg_lo:[0,1] neg_hi:[0,1]
	v_pk_add_f32 v[80:81], v[80:81], v[192:193] op_sel_hi:[1,0] neg_lo:[0,1] neg_hi:[0,1]
	v_add_f32_e32 v172, v172, v192
	v_pk_mul_f32 v[64:65], v[64:65], v[194:195] op_sel_hi:[1,0]
	v_pk_mul_f32 v[62:63], v[62:63], v[194:195] op_sel_hi:[1,0]
	v_pk_mul_f32 v[60:61], v[60:61], v[194:195] op_sel_hi:[1,0]
	v_pk_mul_f32 v[58:59], v[58:59], v[194:195] op_sel_hi:[1,0]
	v_pk_mul_f32 v[56:57], v[56:57], v[194:195] op_sel_hi:[1,0]
	v_pk_mul_f32 v[54:55], v[54:55], v[194:195] op_sel_hi:[1,0]
	v_pk_mul_f32 v[52:53], v[52:53], v[194:195] op_sel_hi:[1,0]
	v_pk_mul_f32 v[50:51], v[50:51], v[194:195] op_sel_hi:[1,0]
	v_pk_mul_f32 v[48:49], v[48:49], v[194:195] op_sel_hi:[1,0]
	v_pk_mul_f32 v[46:47], v[46:47], v[194:195] op_sel_hi:[1,0]
	v_pk_mul_f32 v[44:45], v[44:45], v[194:195] op_sel_hi:[1,0]
	v_pk_mul_f32 v[42:43], v[42:43], v[194:195] op_sel_hi:[1,0]
	v_pk_mul_f32 v[40:41], v[40:41], v[194:195] op_sel_hi:[1,0]
	v_pk_mul_f32 v[38:39], v[38:39], v[194:195] op_sel_hi:[1,0]
	v_pk_mul_f32 v[36:37], v[36:37], v[194:195] op_sel_hi:[1,0]
	v_pk_mul_f32 v[34:35], v[34:35], v[194:195] op_sel_hi:[1,0]
	v_pk_mul_f32 v[32:33], v[32:33], v[194:195] op_sel_hi:[1,0]
	v_pk_mul_f32 v[30:31], v[30:31], v[194:195] op_sel_hi:[1,0]
	v_pk_mul_f32 v[28:29], v[28:29], v[194:195] op_sel_hi:[1,0]
	v_pk_mul_f32 v[26:27], v[26:27], v[194:195] op_sel_hi:[1,0]
	v_pk_mul_f32 v[24:25], v[24:25], v[194:195] op_sel_hi:[1,0]
	v_pk_mul_f32 v[22:23], v[22:23], v[194:195] op_sel_hi:[1,0]
	v_pk_mul_f32 v[20:21], v[20:21], v[194:195] op_sel_hi:[1,0]
	v_pk_mul_f32 v[18:19], v[18:19], v[194:195] op_sel_hi:[1,0]
	v_pk_mul_f32 v[16:17], v[16:17], v[194:195] op_sel_hi:[1,0]
	v_pk_mul_f32 v[14:15], v[14:15], v[194:195] op_sel_hi:[1,0]
	v_pk_mul_f32 v[12:13], v[12:13], v[194:195] op_sel_hi:[1,0]
	v_pk_mul_f32 v[10:11], v[10:11], v[194:195] op_sel_hi:[1,0]
	v_pk_mul_f32 v[8:9], v[8:9], v[194:195] op_sel_hi:[1,0]
	v_pk_mul_f32 v[6:7], v[6:7], v[194:195] op_sel_hi:[1,0]
	v_pk_mul_f32 v[4:5], v[4:5], v[194:195] op_sel_hi:[1,0]
	v_pk_mul_f32 v[2:3], v[2:3], v[194:195] op_sel_hi:[1,0]
	v_mul_f32_e32 v165, v165, v194

; #define LAS __attribute__((address_space(3)))
;     __device__ __forceinline__ static float sg(float g, float uu) { return g * __builtin_amdgcn_rcpf(1.0f + __builtin_amdgcn_exp2f(-1.4426950408889634f * g)) * uu; }
; template <int DQK, int DV, int MODE, bool QNORM, int SK, int NQ> ...
;     ...
;             __builtin_amdgcn_s_setprio(1);
; #pragma unroll
;             for (int d0 = 0; d0 < DQK / 16; ++d0)
; #pragma unroll
;                 for (int sub = 0; sub < NSUB; ++sub) {
;                     const bf16x8 kf = *(const LAS bf16x8*)(sb + (sub * 32 + r32) * KP + hi * 16 + d0 * 32);
; #pragma unroll
;                     for (int qh = 0; qh < NQ; ++qh) sc[qh][sub] = __builtin_amdgcn_mfma_f32_32x32x16_bf16(kf, qf[qh][d0], sc[qh][sub], 0, 0, 0);
;                 }
;             }
;             __builtin_amdgcn_s_setprio(0);
; #pragma unroll
;             for (int sub = 0; sub < NSUB; ++sub) {
;                 const int st = NSUB * sg + sub;
;                 if (QNORM) {
; #pragma unroll
;                     for (int qh = 0; qh < NQ; ++qh)
; #pragma unroll
;                         for (int r = 0; r < 16; ++r) sc[qh][sub][r] = sc[qh][sub][r] * sscale[qh] - m_run[qh];
;     ...
;             for (int qh = 0; qh < NQ; ++qh) {
;                 float tm = sc[qh][0][0];
; #pragma unroll
;                 for (int sub = 0; sub < NSUB; ++sub)
; #pragma unroll
;                     for (int r = 0; r < 16; ++r) tm = fmaxf(tm, sc[qh][sub][r]);
;                 tm = fmaxf(tm, __shfl_xor(tm, 32));
;                 if (__ballot(tm > 0.f) != 0ull) {
;                     const float dl = fmaxf(tm, 0.f); m_run[qh] += dl;
;                     const float alpha = __builtin_amdgcn_exp2f(-dl);
;                     l_run[qh] *= alpha;
; #pragma unroll
;                     for (int sub = 0; sub < NSUB; ++sub)
; #pragma unroll
;                         for (int r = 0; r < 16; ++r) sc[qh][sub][r] -= dl;
; #pragma unroll
;                     for (int dt = 0; dt < DV / 32; ++dt)
; #pragma unroll
;                         for (int r = 0; r < 16; ++r) o[qh][dt][r] *= alpha;
;                 }
.LBB0_4665:
	s_setprio 1
	v_add_u32_e32 v1, v183, v181
	ds_read_b128 v[66:69], v1 offset:27136
	s_waitcnt lgkmcnt(0)
	v_mfma_f32_32x32x16_bf16 v[66:81], v[66:69], v[142:145], 0
	ds_read_b128 v[142:145], v1 offset:27168
	s_waitcnt lgkmcnt(0)
	v_mfma_f32_32x32x16_bf16 v[66:81], v[142:145], v[138:141], v[66:81]
	ds_read_b128 v[138:141], v1 offset:27200
	s_waitcnt lgkmcnt(0)
	v_mfma_f32_32x32x16_bf16 v[66:81], v[138:141], v[134:137], v[66:81]
	ds_read_b128 v[134:137], v1 offset:27232
	s_waitcnt lgkmcnt(0)
	v_mfma_f32_32x32x16_bf16 v[66:81], v[134:137], v[126:129], v[66:81]
	ds_read_b128 v[126:129], v1 offset:27264
	s_waitcnt lgkmcnt(0)
	v_mfma_f32_32x32x16_bf16 v[66:81], v[126:129], v[118:121], v[66:81]
	ds_read_b128 v[118:121], v1 offset:27296
	s_waitcnt lgkmcnt(0)
	v_mfma_f32_32x32x16_bf16 v[66:81], v[118:121], v[110:113], v[66:81]
	ds_read_b128 v[110:113], v1 offset:27328
	s_waitcnt lgkmcnt(0)
	v_mfma_f32_32x32x16_bf16 v[66:81], v[110:113], v[102:105], v[66:81]
	ds_read_b128 v[102:105], v1 offset:27360
	s_waitcnt lgkmcnt(0)
	v_mfma_f32_32x32x16_bf16 v[66:81], v[102:105], v[130:133], v[66:81]
	ds_read_b128 v[102:105], v1 offset:27392
	s_waitcnt lgkmcnt(0)
	v_mfma_f32_32x32x16_bf16 v[66:81], v[102:105], v[122:125], v[66:81]
	ds_read_b128 v[102:105], v1 offset:27424
	s_waitcnt lgkmcnt(0)
	v_mfma_f32_32x32x16_bf16 v[66:81], v[102:105], v[114:117], v[66:81]
	ds_read_b128 v[102:105], v1 offset:27456
	s_waitcnt lgkmcnt(0)
	v_mfma_f32_32x32x16_bf16 v[66:81], v[102:105], v[106:109], v[66:81]
	ds_read_b128 v[102:105], v1 offset:27488
	s_waitcnt lgkmcnt(0)
	v_mfma_f32_32x32x16_bf16 v[66:81], v[102:105], v[98:101], v[66:81]
	ds_read_b128 v[98:101], v1 offset:27520
	s_waitcnt lgkmcnt(0)
	v_mfma_f32_32x32x16_bf16 v[66:81], v[98:101], v[94:97], v[66:81]
	ds_read_b128 v[94:97], v1 offset:27552
	s_waitcnt lgkmcnt(0)
	v_mfma_f32_32x32x16_bf16 v[66:81], v[94:97], v[90:93], v[66:81]
	ds_read_b128 v[90:93], v1 offset:27584
	s_waitcnt lgkmcnt(0)
	v_mfma_f32_32x32x16_bf16 v[66:81], v[90:93], v[86:89], v[66:81]
	ds_read_b128 v[86:89], v1 offset:27616
	s_waitcnt lgkmcnt(0)
	v_mfma_f32_32x32x16_bf16 v[66:81], v[86:89], v[82:85], v[66:81]
	s_setprio 0
	s_nop 10
	v_pk_fma_f32 v[88:89], v[170:171], v[66:67], v[172:173] op_sel_hi:[1,1,0] neg_lo:[0,0,1] neg_hi:[0,0,1]
	v_pk_fma_f32 v[86:87], v[170:171], v[68:69], v[172:173] op_sel_hi:[1,1,0] neg_lo:[0,0,1] neg_hi:[0,0,1]
	v_max_f32_e32 v1, v88, v89
	v_pk_fma_f32 v[84:85], v[170:171], v[70:71], v[172:173] op_sel_hi:[1,1,0] neg_lo:[0,0,1] neg_hi:[0,0,1]
	v_max3_f32 v1, v1, v86, v87
	v_pk_fma_f32 v[82:83], v[170:171], v[72:73], v[172:173] op_sel_hi:[1,1,0] neg_lo:[0,0,1] neg_hi:[0,0,1]
	v_max3_f32 v1, v1, v84, v85
	v_pk_fma_f32 v[72:73], v[170:171], v[74:75], v[172:173] op_sel_hi:[1,1,0] neg_lo:[0,0,1] neg_hi:[0,0,1]
	v_max3_f32 v1, v1, v82, v83
	v_pk_fma_f32 v[70:71], v[170:171], v[76:77], v[172:173] op_sel_hi:[1,1,0] neg_lo:[0,0,1] neg_hi:[0,0,1]
	v_max3_f32 v1, v1, v72, v73
	v_pk_fma_f32 v[68:69], v[170:171], v[78:79], v[172:173] op_sel_hi:[1,1,0] neg_lo:[0,0,1] neg_hi:[0,0,1]
	v_max3_f32 v1, v1, v70, v71
	v_pk_fma_f32 v[66:67], v[170:171], v[80:81], v[172:173] op_sel_hi:[1,1,0] neg_lo:[0,0,1] neg_hi:[0,0,1]
	v_max3_f32 v1, v1, v68, v69
	v_max3_f32 v1, v1, v66, v67
	v_mov_b32_e32 v74, v1
	s_nop 1
	v_permlane32_swap_b32 v74, v1
	s_waitcnt lgkmcnt(0)
	v_max_f32_e32 v74, v74, v74
	v_max_f32_e32 v1, v1, v74
	v_cmp_lt_f32_e32 vcc, 0, v1
	s_cbranch_vccz .LBB0_4641
	v_max_f32_e32 v1, v1, v1
	v_max_f32_e32 v74, 0, v1
	v_exp_f32_e64 v76, -v74
	v_pk_add_f32 v[88:89], v[88:89], v[74:75] op_sel_hi:[1,0] neg_lo:[0,1] neg_hi:[0,1]
	v_pk_add_f32 v[86:87], v[86:87], v[74:75] op_sel_hi:[1,0] neg_lo:[0,1] neg_hi:[0,1]
	v_pk_add_f32 v[84:85], v[84:85], v[74:75] op_sel_hi:[1,0] neg_lo:[0,1] neg_hi:[0,1]
	v_pk_add_f32 v[82:83], v[82:83], v[74:75] op_sel_hi:[1,0] neg_lo:[0,1] neg_hi:[0,1]
	v_pk_add_f32 v[72:73], v[72:73], v[74:75] op_sel_hi:[1,0] neg_lo:[0,1] neg_hi:[0,1]
	v_pk_add_f32 v[70:71], v[70:71], v[74:75] op_sel_hi:[1,0] neg_lo:[0,1] neg_hi:[0,1]
	v_pk_add_f32 v[68:69], v[68:69], v[74:75] op_sel_hi:[1,0] neg_lo:[0,1] neg_hi:[0,1]
	v_pk_add_f32 v[66:67], v[66:67], v[74:75] op_sel_hi:[1,0] neg_lo:[0,1] neg_hi:[0,1]
	v_pk_mul_f32 v[64:65], v[64:65], v[76:77] op_sel_hi:[1,0]
	v_pk_mul_f32 v[62:63], v[62:63], v[76:77] op_sel_hi:[1,0]
	v_pk_mul_f32 v[60:61], v[60:61], v[76:77] op_sel_hi:[1,0]
	v_pk_mul_f32 v[58:59], v[58:59], v[76:77] op_sel_hi:[1,0]
	v_pk_mul_f32 v[56:57], v[56:57], v[76:77] op_sel_hi:[1,0]
	v_pk_mul_f32 v[54:55], v[54:55], v[76:77] op_sel_hi:[1,0]
	v_pk_mul_f32 v[52:53], v[52:53], v[76:77] op_sel_hi:[1,0]
	v_pk_mul_f32 v[50:51], v[50:51], v[76:77] op_sel_hi:[1,0]
	v_pk_mul_f32 v[48:49], v[48:49], v[76:77] op_sel_hi:[1,0]
	v_pk_mul_f32 v[46:47], v[46:47], v[76:77] op_sel_hi:[1,0]
	v_pk_mul_f32 v[44:45], v[44:45], v[76:77] op_sel_hi:[1,0]
	v_pk_mul_f32 v[42:43], v[42:43], v[76:77] op_sel_hi:[1,0]
	v_pk_mul_f32 v[40:41], v[40:41], v[76:77] op_sel_hi:[1,0]
	v_pk_mul_f32 v[38:39], v[38:39], v[76:77] op_sel_hi:[1,0]
	v_pk_mul_f32 v[36:37], v[36:37], v[76:77] op_sel_hi:[1,0]
	v_pk_mul_f32 v[34:35], v[34:35], v[76:77] op_sel_hi:[1,0]
	v_pk_mul_f32 v[32:33], v[32:33], v[76:77] op_sel_hi:[1,0]
	v_pk_mul_f32 v[30:31], v[30:31], v[76:77] op_sel_hi:[1,0]
	v_pk_mul_f32 v[28:29], v[28:29], v[76:77] op_sel_hi:[1,0]
	v_pk_mul_f32 v[26:27], v[26:27], v[76:77] op_sel_hi:[1,0]
	v_pk_mul_f32 v[24:25], v[24:25], v[76:77] op_sel_hi:[1,0]
	v_pk_mul_f32 v[22:23], v[22:23], v[76:77] op_sel_hi:[1,0]
	v_pk_mul_f32 v[20:21], v[20:21], v[76:77] op_sel_hi:[1,0]
	v_pk_mul_f32 v[18:19], v[18:19], v[76:77] op_sel_hi:[1,0]
	v_pk_mul_f32 v[16:17], v[16:17], v[76:77] op_sel_hi:[1,0]
	v_pk_mul_f32 v[14:15], v[14:15], v[76:77] op_sel_hi:[1,0]
	v_pk_mul_f32 v[12:13], v[12:13], v[76:77] op_sel_hi:[1,0]
	v_pk_mul_f32 v[10:11], v[10:11], v[76:77] op_sel_hi:[1,0]
	v_pk_mul_f32 v[8:9], v[8:9], v[76:77] op_sel_hi:[1,0]
	v_pk_mul_f32 v[6:7], v[6:7], v[76:77] op_sel_hi:[1,0]
	v_pk_mul_f32 v[4:5], v[4:5], v[76:77] op_sel_hi:[1,0]
	v_pk_mul_f32 v[2:3], v[2:3], v[76:77] op_sel_hi:[1,0]
	v_mul_f32_e32 v165, v165, v76
	s_branch .LBB0_4641
